# v22 + attention bias-table build batched: 7 bucket loads, 7 table loads, 7 LDS writes instead of 8 serialized dependent load round trips
# baseline (speedup 1.0000x reference)
; __device__ __forceinline__ int ltid(int wave) { int t = (wave << 6) | (int)__builtin_amdgcn_mbcnt_hi(~0u, __builtin_amdgcn_mbcnt_lo(~0u, 0u)); asm volatile("" : "+v"(t)); return t; }
; __device__ void attn_items(const Params& p, unsigned char* shm) {
;     bf16_t* Ks = (bf16_t*)shm;
;     bf16_t* Vt = (bf16_t*)(shm + 36864);
;     bf16_t* Ps = (bf16_t*)(shm + 77824);
;     float* BT = (float*)(shm + 120832);
;     bf16_t* Qb = (bf16_t*)(p.ws + B_Q); const bf16_t* Kb = (const bf16_t*)(p.ws + B_K); const bf16_t* Vb = (const bf16_t*)(p.ws + B_V);
;     float* LSE = (float*)(p.ws + SM_LSE);
;     const int tid = ltid(p.wave), lane = tid & 63, w = tid >> 6, fr = lane & 15, fq = lane >> 4, G_ = gridDim.x;
;     for (int i = tid; i < 24 * 129; i += 512) { const int hd = i / 129, j = i % 129; BT[hd * 132 + j] = p.in[21][(int)BUCKET[hd >> 3][j] * 24 + hd]; }
.LBB0_312:
	s_movk_i32 s0, 0xc18
	s_nop 0
	v_cmp_gt_i32_e32 vcc, s0, v130
	s_and_saveexec_b64 s[0:1], vcc
	s_xor_b64 s[36:37], exec, s[0:1]
	s_cbranch_execz .LBB0_326
	v_readlane_b32 s60, v251, 52
	v_readlane_b32 s61, v251, 53
	v_readlane_b32 s62, v251, 54
	v_readlane_b32 s63, v251, 55
	v_readlane_b32 s64, v251, 56
	v_readlane_b32 s65, v251, 57
	v_readlane_b32 s66, v251, 58
	v_readlane_b32 s67, v251, 59
	v_readlane_b32 s68, v251, 60
	v_readlane_b32 s69, v251, 61
	v_readlane_b32 s70, v251, 62
	v_readlane_b32 s71, v251, 63
	v_readlane_b32 s72, v252, 0
	v_readlane_b32 s73, v252, 1
	v_readlane_b32 s74, v252, 2
	v_readlane_b32 s75, v252, 3
	s_getpc_b64 s[2:3]
	s_add_u32 s2, s2, _ZL6BUCKET@rel32@lo+4
	s_addc_u32 s3, s3, _ZL6BUCKET@rel32@hi+12
	v_mov_b64_e32 v[2:3], s[2:3]
	v_mul_hi_i32 v34, v130, s15
	v_lshrrev_b32_e32 v35, 31, v34
	v_ashrrev_i32_e32 v34, 3, v34
	v_add_u32_e32 v4, v34, v35
	v_lshl_add_u32 v34, v4, 7, v4
	v_sub_u32_e32 v11, v130, v34
	v_ashrrev_i32_e32 v34, 3, v4
	v_mad_i64_i32 v[18:19], s[0:1], v34, s17, v[2:3]
	v_add_co_u32_e32 v18, vcc, v18, v11
	v_addc_co_u32_e32 v19, vcc, 0, v19, vcc
	global_load_ubyte v20, v[18:19], off
	v_add_u32_e32 v18, 0x200, v130
	v_mul_hi_i32 v34, v18, s15
	v_lshrrev_b32_e32 v35, 31, v34
	v_ashrrev_i32_e32 v34, 3, v34
	v_add_u32_e32 v5, v34, v35
	v_lshl_add_u32 v34, v5, 7, v5
	v_sub_u32_e32 v12, v18, v34
	v_ashrrev_i32_e32 v34, 3, v5
	v_mad_i64_i32 v[18:19], s[0:1], v34, s17, v[2:3]
	v_add_co_u32_e32 v18, vcc, v18, v12
	v_addc_co_u32_e32 v19, vcc, 0, v19, vcc
	global_load_ubyte v21, v[18:19], off
	v_add_u32_e32 v18, 0x400, v130
	v_mul_hi_i32 v34, v18, s15
	v_lshrrev_b32_e32 v35, 31, v34
	v_ashrrev_i32_e32 v34, 3, v34
	v_add_u32_e32 v6, v34, v35
	v_lshl_add_u32 v34, v6, 7, v6
	v_sub_u32_e32 v13, v18, v34
	v_ashrrev_i32_e32 v34, 3, v6
	v_mad_i64_i32 v[18:19], s[0:1], v34, s17, v[2:3]
	v_add_co_u32_e32 v18, vcc, v18, v13
	v_addc_co_u32_e32 v19, vcc, 0, v19, vcc
	global_load_ubyte v22, v[18:19], off
	v_add_u32_e32 v18, 0x600, v130
	v_mul_hi_i32 v34, v18, s15
	v_lshrrev_b32_e32 v35, 31, v34
	v_ashrrev_i32_e32 v34, 3, v34
	v_add_u32_e32 v7, v34, v35
	v_lshl_add_u32 v34, v7, 7, v7
	v_sub_u32_e32 v14, v18, v34
	v_ashrrev_i32_e32 v34, 3, v7
	v_mad_i64_i32 v[18:19], s[0:1], v34, s17, v[2:3]
	v_add_co_u32_e32 v18, vcc, v18, v14
	v_addc_co_u32_e32 v19, vcc, 0, v19, vcc
	global_load_ubyte v23, v[18:19], off
	v_add_u32_e32 v18, 0x800, v130
	v_mul_hi_i32 v34, v18, s15
	v_lshrrev_b32_e32 v35, 31, v34
	v_ashrrev_i32_e32 v34, 3, v34
	v_add_u32_e32 v8, v34, v35
	v_lshl_add_u32 v34, v8, 7, v8
	v_sub_u32_e32 v15, v18, v34
	v_ashrrev_i32_e32 v34, 3, v8
	v_mad_i64_i32 v[18:19], s[0:1], v34, s17, v[2:3]
	v_add_co_u32_e32 v18, vcc, v18, v15
	v_addc_co_u32_e32 v19, vcc, 0, v19, vcc
	global_load_ubyte v24, v[18:19], off
	v_add_u32_e32 v18, 0xa00, v130
	v_mul_hi_i32 v34, v18, s15
	v_lshrrev_b32_e32 v35, 31, v34
	v_ashrrev_i32_e32 v34, 3, v34
	v_add_u32_e32 v9, v34, v35
	v_lshl_add_u32 v34, v9, 7, v9
	v_sub_u32_e32 v16, v18, v34
	v_ashrrev_i32_e32 v34, 3, v9
	v_mad_i64_i32 v[18:19], s[0:1], v34, s17, v[2:3]
	v_add_co_u32_e32 v18, vcc, v18, v16
	v_addc_co_u32_e32 v19, vcc, 0, v19, vcc
	global_load_ubyte v25, v[18:19], off
	v_add_u32_e32 v18, 0xc00, v130
	v_min_u32_e32 v18, 0xc17, v18
	v_mul_hi_i32 v34, v18, s15
	v_lshrrev_b32_e32 v35, 31, v34
	v_ashrrev_i32_e32 v34, 3, v34
	v_add_u32_e32 v10, v34, v35
	v_lshl_add_u32 v34, v10, 7, v10
	v_sub_u32_e32 v17, v18, v34
	v_ashrrev_i32_e32 v34, 3, v10
	v_mad_i64_i32 v[18:19], s[0:1], v34, s17, v[2:3]
	v_add_co_u32_e32 v18, vcc, v18, v17
	v_addc_co_u32_e32 v19, vcc, 0, v19, vcc
	global_load_ubyte v26, v[18:19], off
	s_movk_i32 s2, 0x210
	s_waitcnt vmcnt(6)
	v_mad_u32_u24 v18, v20, 24, v4
	v_ashrrev_i32_e32 v19, 31, v18
	v_lshl_add_u64 v[18:19], v[18:19], 2, s[70:71]
	global_load_dword v27, v[18:19], off
	v_mul_lo_u32 v34, v4, s2
	v_lshlrev_b32_e32 v11, 2, v11
	v_add3_u32 v11, s22, v34, v11
	s_waitcnt vmcnt(6)
	v_mad_u32_u24 v18, v21, 24, v5
	v_ashrrev_i32_e32 v19, 31, v18
	v_lshl_add_u64 v[18:19], v[18:19], 2, s[70:71]
	global_load_dword v28, v[18:19], off
	v_mul_lo_u32 v34, v5, s2
	v_lshlrev_b32_e32 v12, 2, v12
	v_add3_u32 v12, s22, v34, v12
	s_waitcnt vmcnt(6)
	v_mad_u32_u24 v18, v22, 24, v6
	v_ashrrev_i32_e32 v19, 31, v18
	v_lshl_add_u64 v[18:19], v[18:19], 2, s[70:71]
	global_load_dword v29, v[18:19], off
	v_mul_lo_u32 v34, v6, s2
	v_lshlrev_b32_e32 v13, 2, v13
	v_add3_u32 v13, s22, v34, v13
	s_waitcnt vmcnt(6)
	v_mad_u32_u24 v18, v23, 24, v7
	v_ashrrev_i32_e32 v19, 31, v18
	v_lshl_add_u64 v[18:19], v[18:19], 2, s[70:71]
	global_load_dword v30, v[18:19], off
	v_mul_lo_u32 v34, v7, s2
	v_lshlrev_b32_e32 v14, 2, v14
	v_add3_u32 v14, s22, v34, v14
	s_waitcnt vmcnt(6)
	v_mad_u32_u24 v18, v24, 24, v8
	v_ashrrev_i32_e32 v19, 31, v18
	v_lshl_add_u64 v[18:19], v[18:19], 2, s[70:71]
	global_load_dword v31, v[18:19], off
	v_mul_lo_u32 v34, v8, s2
	v_lshlrev_b32_e32 v15, 2, v15
	v_add3_u32 v15, s22, v34, v15
	s_waitcnt vmcnt(6)
	v_mad_u32_u24 v18, v25, 24, v9
	v_ashrrev_i32_e32 v19, 31, v18
	v_lshl_add_u64 v[18:19], v[18:19], 2, s[70:71]
	global_load_dword v32, v[18:19], off
	v_mul_lo_u32 v34, v9, s2
	v_lshlrev_b32_e32 v16, 2, v16
	v_add3_u32 v16, s22, v34, v16
	s_waitcnt vmcnt(6)
	v_mad_u32_u24 v18, v26, 24, v10
	v_ashrrev_i32_e32 v19, 31, v18
	v_lshl_add_u64 v[18:19], v[18:19], 2, s[70:71]
	global_load_dword v33, v[18:19], off
	v_mul_lo_u32 v34, v10, s2
	v_lshlrev_b32_e32 v17, 2, v17
	v_add3_u32 v17, s22, v34, v17
	s_waitcnt vmcnt(6)
	ds_write_b32 v11, v27
	s_waitcnt vmcnt(5)
	ds_write_b32 v12, v28
	s_waitcnt vmcnt(4)
	ds_write_b32 v13, v29
	s_waitcnt vmcnt(3)
	ds_write_b32 v14, v30
	s_waitcnt vmcnt(2)
	ds_write_b32 v15, v31
	s_waitcnt vmcnt(1)
	ds_write_b32 v16, v32
	s_waitcnt vmcnt(0)
	ds_write_b32 v17, v33
